# followers also start an L2 write-back at arrival so the XCC leader's final write-back has less left
# baseline (speedup 1.0000x reference)
.Lxbar_follow:
	buffer_wbl2 sc1
	s_movk_i32 s99, 0x552
	s_bitcmp1_b32 s99, s98
	s_cbranch_scc1 .Lxbar_noinv
	buffer_inv sc1
